# fox_prompt PV: 12 of 16 V-transpose fragments prefetched into dead K-fragment registers under the softmax, PV MFMAs back-to-back
# speedup vs baseline: 1.0117x; 1.0035x over previous
; #define LAS __attribute__((address_space(3)))
; __device__ __forceinline__ unsigned pkbf(float lo, float hi) { f32x2 v = {lo, hi}; bf16x2_t b = __builtin_convertvector(v, bf16x2_t); return __builtin_bit_cast(unsigned, b); }
; __device__ __forceinline__ s16x4 lds_tr(LAS const char* p) { return __builtin_bit_cast(s16x4, __builtin_amdgcn_ds_read_tr16_b64_v4i16((LAS s16x4*)p)); }
; __device__ __forceinline__ bf16x8 cat44(s16x4 a, s16x4 b) { return (bf16x8){a[0], a[1], a[2], a[3], b[0], b[1], b[2], b[3]}; }
; __device__ __forceinline__ float fexp2(float x) { return __builtin_amdgcn_exp2f(x); }
; __device__ __forceinline__ void fox_prompt_unit(LAS char* L, const bf16_t* P, const float* lfT, bf16_t* MIX, int b, int h, int qb, const int wv) {
;     ...
;             float mx = fmaxf(s0[0], s1[0]);
; #pragma unroll
;             for (int r = 1; r < 16; ++r) mx = fmaxf(mx, fmaxf(s0[r], s1[r]));
;             mx = xmax32(mx);
;             const float mn = fmaxf(m, mx), alpha = fexp2(m - mn); m = mn;
;             float ls = 0.f;
; #pragma unroll
;             for (int r = 0; r < 16; ++r) { s0[r] = fexp2(s0[r] - mn); s1[r] = fexp2(s1[r] - mn); ls += s0[r] + s1[r]; }
;             l = l * alpha + ls;
; #pragma unroll
;             for (int d = 0; d < 4; ++d)
; #pragma unroll
;                 for (int r = 0; r < 16; ++r) o[d][r] *= alpha;
;             bf16x8 pf[4];
;             { u32x4 w;
;               w.x = pkbf(s0[0], s0[1]); w.y = pkbf(s0[2], s0[3]); w.z = pkbf(s0[4], s0[5]); w.w = pkbf(s0[6], s0[7]); pf[0] = __builtin_bit_cast(bf16x8, w);
;               w.x = pkbf(s0[8], s0[9]); w.y = pkbf(s0[10], s0[11]); w.z = pkbf(s0[12], s0[13]); w.w = pkbf(s0[14], s0[15]); pf[1] = __builtin_bit_cast(bf16x8, w);
;               w.x = pkbf(s1[0], s1[1]); w.y = pkbf(s1[2], s1[3]); w.z = pkbf(s1[4], s1[5]); w.w = pkbf(s1[6], s1[7]); pf[2] = __builtin_bit_cast(bf16x8, w);
;               w.x = pkbf(s1[8], s1[9]); w.y = pkbf(s1[10], s1[11]); w.z = pkbf(s1[12], s1[13]); w.w = pkbf(s1[14], s1[15]); pf[3] = __builtin_bit_cast(bf16x8, w); }
; #pragma unroll
;             for (int ss = 0; ss < 4; ++ss)
; #pragma unroll
;                 for (int d = 0; d < 4; ++d) { LAS const char* vp = Vb + (16 * ss + 4 * hi + (i16 >> 2)) * AVP + (32 * d + 16 * cb + 4 * (i16 & 3)) * 2;
;                     o[d] = mfma32(cat44(lds_tr(vp), lds_tr(vp + 8 * AVP)), pf[ss], o[d]); }
.LBB0_202:
	s_mulk_i32 s17, 0x5000
	v_add_u32_e32 v248, s17, v172
	ds_read_b64_tr_b16 v[200:201], v248 offset:34816
	ds_read_b64_tr_b16 v[202:203], v248 offset:37376
	ds_read_b64_tr_b16 v[204:205], v248 offset:34880
	ds_read_b64_tr_b16 v[206:207], v248 offset:37440
	ds_read_b64_tr_b16 v[208:209], v248 offset:34944
	ds_read_b64_tr_b16 v[210:211], v248 offset:37504
	ds_read_b64_tr_b16 v[212:213], v248 offset:35008
	ds_read_b64_tr_b16 v[214:215], v248 offset:37568
	ds_read_b64_tr_b16 v[216:217], v248 offset:39936
	ds_read_b64_tr_b16 v[218:219], v248 offset:42496
	ds_read_b64_tr_b16 v[220:221], v248 offset:40000
	ds_read_b64_tr_b16 v[222:223], v248 offset:42560
	s_nop 5
	v_max_f32_e32 v0, v67, v67
	v_max_f32_e32 v146, v83, v83
	v_max_f32_e32 v0, v146, v0
	v_max_f32_e32 v146, v68, v68
	v_max_f32_e32 v147, v84, v84
	v_max_f32_e32 v146, v147, v146
	v_max_f32_e32 v147, v69, v69
	v_max_f32_e32 v148, v85, v85
	v_max3_f32 v0, v82, v66, v0
	v_max_f32_e32 v147, v148, v147
	v_max3_f32 v0, v0, v146, v147
	v_max_f32_e32 v146, v70, v70
	v_max_f32_e32 v147, v86, v86
	v_max_f32_e32 v146, v147, v146
	v_max_f32_e32 v147, v71, v71
	v_max_f32_e32 v148, v87, v87
	v_max_f32_e32 v147, v148, v147
	v_max3_f32 v0, v0, v146, v147
	v_max_f32_e32 v146, v72, v72
	v_max_f32_e32 v147, v88, v88
	v_max_f32_e32 v146, v147, v146
	v_max_f32_e32 v147, v73, v73
	v_max_f32_e32 v148, v89, v89
	v_max_f32_e32 v147, v148, v147
	v_max3_f32 v0, v0, v146, v147
	v_max_f32_e32 v146, v74, v74
	v_max_f32_e32 v147, v90, v90
	v_max_f32_e32 v146, v147, v146
	v_max_f32_e32 v147, v75, v75
	v_max_f32_e32 v148, v91, v91
	v_max_f32_e32 v147, v148, v147
	v_max3_f32 v0, v0, v146, v147
	v_max_f32_e32 v146, v76, v76
	v_max_f32_e32 v147, v92, v92
	v_max_f32_e32 v146, v147, v146
	v_max_f32_e32 v147, v77, v77
	v_max_f32_e32 v148, v93, v93
	v_max_f32_e32 v147, v148, v147
	v_max3_f32 v0, v0, v146, v147
	v_max_f32_e32 v146, v78, v78
	v_max_f32_e32 v147, v94, v94
	v_max_f32_e32 v146, v147, v146
	v_max_f32_e32 v147, v79, v79
	v_max_f32_e32 v148, v95, v95
	v_max_f32_e32 v147, v148, v147
	v_max3_f32 v0, v0, v146, v147
	v_max_f32_e32 v146, v80, v80
	v_max_f32_e32 v147, v96, v96
	v_max_f32_e32 v146, v147, v146
	v_max_f32_e32 v147, v81, v81
	v_max_f32_e32 v148, v97, v97
	v_max_f32_e32 v147, v148, v147
	v_max3_f32 v0, v0, v146, v147
	v_mov_b32_e32 v146, v0
	ds_read_b64_tr_b16 v[224:225], v248 offset:40064
	ds_read_b64_tr_b16 v[226:227], v248 offset:42624
	ds_read_b64_tr_b16 v[228:229], v248 offset:40128
	ds_read_b64_tr_b16 v[230:231], v248 offset:42688
	ds_read_b64_tr_b16 v[232:233], v248 offset:45056
	ds_read_b64_tr_b16 v[234:235], v248 offset:47616
	ds_read_b64_tr_b16 v[236:237], v248 offset:45120
	ds_read_b64_tr_b16 v[238:239], v248 offset:47680
	ds_read_b64_tr_b16 v[240:241], v248 offset:45248
	ds_read_b64_tr_b16 v[242:243], v248 offset:47808
	ds_read_b64_tr_b16 v[244:245], v248 offset:45184
	ds_read_b64_tr_b16 v[246:247], v248 offset:47744
	s_nop 1
	v_permlane32_swap_b32_e32 v0, v146
	v_max3_f32 v178, v158, v0, v146
	v_sub_f32_e32 v0, v82, v178
	v_sub_f32_e32 v68, v68, v178
	v_exp_f32_e32 v146, v0
	v_sub_f32_e32 v0, v66, v178
	v_sub_f32_e32 v82, v84, v178
	v_exp_f32_e32 v179, v68
	v_sub_f32_e32 v68, v87, v178
	v_exp_f32_e32 v163, v0
	v_sub_f32_e32 v0, v83, v178
	v_exp_f32_e32 v147, v82
	v_exp_f32_e32 v82, v68
	v_sub_f32_e32 v68, v88, v178
	v_sub_f32_e32 v66, v158, v178
	v_exp_f32_e32 v158, v0
	v_sub_f32_e32 v0, v67, v178
	v_sub_f32_e32 v67, v85, v178
	v_exp_f32_e32 v85, v68
	v_sub_f32_e32 v68, v72, v178
	v_exp_f32_e32 v160, v67
	v_sub_f32_e32 v67, v69, v178
	v_exp_f32_e32 v69, v68
	v_sub_f32_e32 v68, v89, v178
	v_exp_f32_e32 v84, v68
	v_sub_f32_e32 v68, v90, v178
	v_exp_f32_e32 v162, v67
	v_sub_f32_e32 v67, v86, v178
	v_exp_f32_e32 v190, v68
	v_sub_f32_e32 v68, v91, v178
	v_exp_f32_e32 v83, v67
	v_sub_f32_e32 v67, v70, v178
	v_exp_f32_e32 v70, v68
	v_sub_f32_e32 v68, v92, v178
	v_exp_f32_e32 v91, v68
	v_sub_f32_e32 v68, v93, v178
	v_exp_f32_e32 v72, v68
	v_sub_f32_e32 v68, v94, v178
	v_sub_f32_e32 v86, v96, v178
	v_add_u32_e32 v92, s17, v172
	v_exp_f32_e32 v67, v67
	v_exp_f32_e32 v87, v68
	v_sub_f32_e32 v68, v95, v178
	v_exp_f32_e32 v66, v66
	v_exp_f32_e32 v89, v86
	v_sub_f32_e32 v86, v97, v178
	ds_read_b64_tr_b16 v[94:95], v92 offset:50176
	ds_read_b64_tr_b16 v[96:97], v92 offset:52736
	ds_read_b64_tr_b16 v[196:197], v92 offset:50240
	ds_read_b64_tr_b16 v[198:199], v92 offset:52800
	v_pk_mul_f32 v[64:65], v[64:65], v[66:67] op_sel_hi:[1,0]
	v_pk_mul_f32 v[62:63], v[62:63], v[66:67] op_sel_hi:[1,0]
	v_pk_mul_f32 v[60:61], v[60:61], v[66:67] op_sel_hi:[1,0]
	v_pk_mul_f32 v[58:59], v[58:59], v[66:67] op_sel_hi:[1,0]
	v_pk_mul_f32 v[56:57], v[56:57], v[66:67] op_sel_hi:[1,0]
	v_pk_mul_f32 v[54:55], v[54:55], v[66:67] op_sel_hi:[1,0]
	v_pk_mul_f32 v[52:53], v[52:53], v[66:67] op_sel_hi:[1,0]
	v_pk_mul_f32 v[50:51], v[50:51], v[66:67] op_sel_hi:[1,0]
	v_pk_mul_f32 v[48:49], v[48:49], v[66:67] op_sel_hi:[1,0]
	v_pk_mul_f32 v[46:47], v[46:47], v[66:67] op_sel_hi:[1,0]
	v_pk_mul_f32 v[44:45], v[44:45], v[66:67] op_sel_hi:[1,0]
	v_pk_mul_f32 v[42:43], v[42:43], v[66:67] op_sel_hi:[1,0]
	v_pk_mul_f32 v[40:41], v[40:41], v[66:67] op_sel_hi:[1,0]
	v_pk_mul_f32 v[38:39], v[38:39], v[66:67] op_sel_hi:[1,0]
	v_pk_mul_f32 v[36:37], v[36:37], v[66:67] op_sel_hi:[1,0]
	v_pk_mul_f32 v[34:35], v[34:35], v[66:67] op_sel_hi:[1,0]
	v_cvt_pk_bf16_f32 v192, v146, v158
	v_cvt_pk_bf16_f32 v193, v147, v160
	v_cvt_pk_bf16_f32 v194, v83, v82
	v_cvt_pk_bf16_f32 v195, v85, v84
	v_pk_mul_f32 v[32:33], v[32:33], v[66:67] op_sel_hi:[1,0]
	v_pk_mul_f32 v[30:31], v[30:31], v[66:67] op_sel_hi:[1,0]
	s_waitcnt lgkmcnt(4)
; #define LAS __attribute__((address_space(3)))
; __device__ __forceinline__ unsigned pkbf(float lo, float hi) { f32x2 v = {lo, hi}; bf16x2_t b = __builtin_convertvector(v, bf16x2_t); return __builtin_bit_cast(unsigned, b); }
; __device__ __forceinline__ s16x4 lds_tr(LAS const char* p) { return __builtin_bit_cast(s16x4, __builtin_amdgcn_ds_read_tr16_b64_v4i16((LAS s16x4*)p)); }
; __device__ __forceinline__ bf16x8 cat44(s16x4 a, s16x4 b) { return (bf16x8){a[0], a[1], a[2], a[3], b[0], b[1], b[2], b[3]}; }
; __device__ __forceinline__ f32x16 mfma32(bf16x8 a, bf16x8 b, f32x16 c) { return __builtin_amdgcn_mfma_f32_32x32x16_bf16(a, b, c, 0, 0, 0); }
; __device__ __forceinline__ float fexp2(float x) { return __builtin_amdgcn_exp2f(x); }
; __device__ __forceinline__ void fox_prompt_unit(LAS char* L, const bf16_t* P, const float* lfT, bf16_t* MIX, int b, int h, int qb, const int wv) {
;     ...
;             float ls = 0.f;
; #pragma unroll
;             for (int r = 0; r < 16; ++r) { s0[r] = fexp2(s0[r] - mn); s1[r] = fexp2(s1[r] - mn); ls += s0[r] + s1[r]; }
;             l = l * alpha + ls;
; #pragma unroll
;             for (int d = 0; d < 4; ++d)
; #pragma unroll
;                 for (int r = 0; r < 16; ++r) o[d][r] *= alpha;
;             bf16x8 pf[4];
;             { u32x4 w;
;               w.x = pkbf(s0[0], s0[1]); w.y = pkbf(s0[2], s0[3]); w.z = pkbf(s0[4], s0[5]); w.w = pkbf(s0[6], s0[7]); pf[0] = __builtin_bit_cast(bf16x8, w);
;               w.x = pkbf(s0[8], s0[9]); w.y = pkbf(s0[10], s0[11]); w.z = pkbf(s0[12], s0[13]); w.w = pkbf(s0[14], s0[15]); pf[1] = __builtin_bit_cast(bf16x8, w);
;               w.x = pkbf(s1[0], s1[1]); w.y = pkbf(s1[2], s1[3]); w.z = pkbf(s1[4], s1[5]); w.w = pkbf(s1[6], s1[7]); pf[2] = __builtin_bit_cast(bf16x8, w);
;               w.x = pkbf(s1[8], s1[9]); w.y = pkbf(s1[10], s1[11]); w.z = pkbf(s1[12], s1[13]); w.w = pkbf(s1[14], s1[15]); pf[3] = __builtin_bit_cast(bf16x8, w); }
; #pragma unroll
;             for (int ss = 0; ss < 4; ++ss)
; #pragma unroll
;                 for (int d = 0; d < 4; ++d) { LAS const char* vp = Vb + (16 * ss + 4 * hi + (i16 >> 2)) * AVP + (32 * d + 16 * cb + 4 * (i16 & 3)) * 2;
;                     o[d] = mfma32(cat44(lds_tr(vp), lds_tr(vp + 8 * AVP)), pf[ss], o[d]); }
	v_mfma_f32_32x32x16_bf16 v[50:65], v[200:203], v[192:195], v[50:65]
	v_mul_f32_e64 v28, v28, v66
	v_mul_f32_e64 v29, v29, v66
	v_mul_f32_e64 v26, v26, v66
	v_mul_f32_e64 v27, v27, v66
	v_pk_mul_f32 v[24:25], v[24:25], v[66:67] op_sel_hi:[1,0]
	v_pk_mul_f32 v[22:23], v[22:23], v[66:67] op_sel_hi:[1,0]
	v_pk_mul_f32 v[20:21], v[20:21], v[66:67] op_sel_hi:[1,0]
	v_pk_mul_f32 v[18:19], v[18:19], v[66:67] op_sel_hi:[1,0]
	v_mfma_f32_32x32x16_bf16 v[34:49], v[204:207], v[192:195], v[34:49]
	v_mul_f32_e64 v16, v16, v66
	v_mul_f32_e64 v17, v17, v66
	v_mul_f32_e64 v14, v14, v66
	v_mul_f32_e64 v15, v15, v66
	v_pk_mul_f32 v[12:13], v[12:13], v[66:67] op_sel_hi:[1,0]
	v_pk_mul_f32 v[10:11], v[10:11], v[66:67] op_sel_hi:[1,0]
	v_pk_mul_f32 v[8:9], v[8:9], v[66:67] op_sel_hi:[1,0]
	v_pk_mul_f32 v[6:7], v[6:7], v[66:67] op_sel_hi:[1,0]
	v_pk_mul_f32 v[4:5], v[4:5], v[66:67] op_sel_hi:[1,0]
	v_pk_mul_f32 v[2:3], v[2:3], v[66:67] op_sel_hi:[1,0]
	v_exp_f32_e32 v68, v68
	v_mfma_f32_32x32x16_bf16 v[18:33], v[208:211], v[192:195], v[18:33]
	v_exp_f32_e32 v86, v86
	v_sub_f32_e32 v71, v71, v178
	v_exp_f32_e32 v88, v71
	v_exp_f32_e32 v0, v0
	v_sub_f32_e32 v71, v73, v178
	v_exp_f32_e32 v90, v71
	v_mfma_f32_32x32x16_bf16 v[2:17], v[212:215], v[192:195], v[2:17]
	v_cvt_pk_bf16_f32 v192, v190, v70
	v_cvt_pk_bf16_f32 v193, v91, v72
	v_cvt_pk_bf16_f32 v194, v87, v68
	v_cvt_pk_bf16_f32 v195, v89, v86
	v_sub_f32_e32 v71, v74, v178
	v_exp_f32_e32 v93, v71
	v_mfma_f32_32x32x16_bf16 v[50:65], v[216:219], v[192:195], v[50:65]
	v_add_f32_e32 v159, v146, v163
	v_add_f32_e32 v83, v83, v67
	v_sub_f32_e32 v71, v76, v178
	v_sub_f32_e32 v76, v79, v178
	v_sub_f32_e32 v73, v75, v178
	v_sub_f32_e32 v75, v78, v178
	v_mfma_f32_32x32x16_bf16 v[34:49], v[220:223], v[192:195], v[34:49]
	v_exp_f32_e32 v148, v76
	v_sub_f32_e32 v76, v81, v178
	v_exp_f32_e32 v75, v75
	v_add_f32_e32 v161, v147, v179
	v_exp_f32_e32 v147, v71
	v_add_f32_e32 v71, v190, v93
	v_mfma_f32_32x32x16_bf16 v[18:33], v[224:227], v[192:195], v[18:33]
	v_cvt_pk_bf16_f32 v190, v163, v0
	v_add_f32_e32 v85, v85, v69
	v_cvt_pk_bf16_f32 v191, v179, v162
	v_exp_f32_e32 v74, v73
	v_add_f32_e32 v73, v91, v147
	v_mfma_f32_32x32x16_bf16 v[2:17], v[228:231], v[192:195], v[2:17]
	v_cvt_pk_bf16_f32 v192, v67, v88
	v_sub_f32_e32 v67, v77, v178
	v_exp_f32_e32 v146, v67
	v_sub_f32_e32 v67, v80, v178
	v_pk_add_f32 v[80:81], v[158:159], v[0:1]
	v_exp_f32_e32 v67, v67
	v_pk_add_f32 v[80:81], v[80:81], v[80:81] op_sel_hi:[0,1]
	v_mov_b32_e32 v163, v81
	v_pk_add_f32 v[80:81], v[160:161], v[162:163]
	v_cvt_pk_bf16_f32 v193, v69, v90
	v_pk_add_f32 v[80:81], v[80:81], v[80:81] op_sel_hi:[0,1]
	v_add_f32_e32 v69, v87, v75
	v_add_f32_e32 v87, v89, v67
	v_mov_b32_e32 v89, v81
	v_mfma_f32_32x32x16_bf16 v[50:65], v[232:235], v[190:193], v[50:65]
	v_add_f32_e64 v80, v82, v88
	v_add_f32_e64 v81, v83, v89
	v_pk_add_f32 v[80:81], v[80:81], v[80:81] op_sel_hi:[0,1]
	v_mov_b32_e32 v91, v81
	v_pk_add_f32 v[80:81], v[84:85], v[90:91]
	v_mfma_f32_32x32x16_bf16 v[34:49], v[236:239], v[190:193], v[34:49]
	v_exp_f32_e32 v194, v76
	v_pk_add_f32 v[84:85], v[80:81], v[80:81] op_sel_hi:[0,1]
	v_mfma_f32_32x32x16_bf16 v[2:17], v[240:243], v[190:193], v[2:17]
	v_cvt_pk_bf16_f32 v78, v75, v148
	v_mov_b32_e32 v75, v85
	v_add_f32_e64 v70, v70, v74
	v_add_f32_e64 v71, v71, v75
	v_cvt_pk_bf16_f32 v77, v147, v146
	v_pk_add_f32 v[70:71], v[70:71], v[70:71] op_sel_hi:[0,1]
	v_mov_b32_e32 v147, v71
	v_cvt_pk_bf16_f32 v76, v93, v74
	v_mfma_f32_32x32x16_bf16 v[18:33], v[244:247], v[190:193], v[18:33]
	ds_read_b64_tr_b16 v[80:81], v92 offset:50304
	ds_read_b64_tr_b16 v[82:83], v92 offset:52864
	v_pk_add_f32 v[74:75], v[72:73], v[146:147]
	ds_read_b64_tr_b16 v[70:71], v92 offset:50368
	ds_read_b64_tr_b16 v[72:73], v92 offset:52928
	v_cvt_pk_bf16_f32 v79, v67, v194
	v_pk_add_f32 v[74:75], v[74:75], v[74:75] op_sel_hi:[0,1]
	v_mov_b32_e32 v149, v75
	s_waitcnt lgkmcnt(4)
	v_mfma_f32_32x32x16_bf16 v[50:65], v[94:97], v[76:79], v[50:65]
	v_add_f32_e64 v68, v68, v148
	v_add_f32_e64 v69, v69, v149
	v_pk_add_f32 v[68:69], v[68:69], v[68:69] op_sel_hi:[0,1]
	v_mov_b32_e32 v195, v69
	v_pk_add_f32 v[68:69], v[86:87], v[194:195]
	s_nop 0
	v_add_f32_e32 v0, v68, v69
	s_waitcnt lgkmcnt(4)
	v_mfma_f32_32x32x16_bf16 v[34:49], v[196:199], v[76:79], v[34:49]
	v_fmac_f32_e32 v0, v177, v66
	v_mov_b32_e32 v158, v178
	v_mov_b32_e32 v177, v0
	s_waitcnt lgkmcnt(2)
	v_mfma_f32_32x32x16_bf16 v[18:33], v[80:83], v[76:79], v[18:33]
	s_waitcnt lgkmcnt(0)
	v_mfma_f32_32x32x16_bf16 v[2:17], v[70:73], v[76:79], v[2:17]
